# version 69 plus the software-pipelined phase-0 weight conversion (double-buffered sub-item loads, wait counts only the current loads)
# baseline (speedup 1.0000x reference)
.LBB0_25:
	s_lshl_b32 s0, s2, 3
	s_add_i32 s3, s31, s0
	s_mov_b32 s96, s31
	s_cmpk_gt_i32 s3, 0x50ff
	s_cbranch_scc1 .LBB0_39
	s_cmp_lg_u32 s33, 0x100
	s_cbranch_scc1 .Lp0_old
	v_readlane_b32 s22, v255, 14
	v_readlane_b32 s23, v255, 15
	v_readlane_b32 s24, v255, 34
	v_readlane_b32 s25, v255, 35
	v_lshrrev_b32_e32 v79, 5, v174
	v_and_b32_e32 v80, 31, v174
	v_mul_u32_u24_e32 v67, 0x13000, v79
	v_lshl_add_u32 v67, v80, 2, v67
	v_mul_u32_u24_e32 v68, 0x15800, v79
	v_lshl_add_u32 v68, v80, 2, v68
	v_lshrrev_b32_e32 v81, 3, v174
	v_and_b32_e32 v82, 7, v174
	v_lshlrev_b32_e32 v69, 13, v81
	v_lshl_add_u32 v69, v82, 4, v69
	s_mul_i32 s0, s96, 0x3000
	s_add_u32 s0, s0, 0x2000
	v_mul_u32_u24_e32 v83, 33, v79
	v_add_u32_e32 v83, v83, v80
	v_lshl_add_u32 v71, v83, 2, s0
	v_add_u32_e32 v72, 0x420, v71
	v_add_u32_e32 v73, 0x840, v71
	v_add_u32_e32 v74, 0xc60, v71
	v_add_u32_e32 v75, 0x1080, v71
	v_add_u32_e32 v76, 0x14a0, v71
	v_add_u32_e32 v77, 0x18c0, v71
	v_add_u32_e32 v78, 0x1ce0, v71
	v_mul_u32_u24_e32 v83, 264, v82
	v_add_u32_e32 v83, v83, v81
	v_lshl_add_u32 v70, v83, 2, s0
.Lp0n_top:
	s_lshl_b32 s3, s2, 3
	s_add_u32 s3, s3, s96
	s_mov_b32 s1, 0
	s_lshl_b32 s16, s1, 6
	s_cmp_lt_u32 s3, 0x2600
	s_cbranch_scc0 .Lp0_up0
	s_mul_hi_u32 s7, s3, 0x6bca1b
	s_mul_i32 s8, s7, 608
	s_sub_u32 s8, s3, s8
	s_lshl_b32 s9, s7, 8
	s_add_u32 s9, s9, s16
	s_mul_i32 s16, s9, 0x13000
	s_lshl_b32 s17, s8, 7
	s_add_u32 s16, s16, s17
	s_add_u32 s4, s22, s16
	s_addc_u32 s5, s23, 0
	s_mov_b32 s6, 0x26000
	v_mov_b32_e32 v66, v67
	s_lshl_b32 s16, s8, 18
	s_lshl_b32 s17, s9, 1
	s_add_u32 s16, s16, s17
	s_add_u32 s16, s16, 0x1200000
	s_add_u32 s12, s70, s16
	s_addc_u32 s13, s71, 0
	s_branch .Lp0_ad0
